# FFT final loop: the skip-coefficient load issued with the early first-iteration loads (landing v156:157) instead of right after the barrier
# speedup vs baseline: 1.0007x; 1.0007x over previous
.LBB0_703:
	s_or_b64 exec, exec, s[2:3]
	s_waitcnt vmcnt(0)
	s_lshl_b64 s[98:99], s[28:29], 13
	s_lshl_b64 s[100:101], s[10:11], 13
	v_add_u32_e32 v152, 0, v24
	v_ashrrev_i32_e32 v153, 31, v152
	v_lshlrev_b64 v[148:149], 1, v[152:153]
	v_lshl_add_u64 v[150:151], s[30:31], 0, v[148:149]
	global_load_ushort v116, v[150:151], off
	v_add_u32_e32 v150, 0, v24
	v_ashrrev_i32_e32 v151, 31, v150
	v_lshl_add_u64 v[148:149], s[98:99], 0, v[150:151]
	v_lshl_add_u64 v[148:149], v[148:149], 1, s[0:1]
	global_load_ushort v117, v[148:149], off
	v_add_u32_e32 v150, 0, v24
	v_ashrrev_i32_e32 v151, 31, v150
	v_lshlrev_b64 v[148:149], 1, v[150:151]
	v_lshl_add_u64 v[148:149], s[86:87], 0, v[148:149]
	global_load_ushort v118, v[148:149], off
	v_add_u32_e32 v152, 0, v24
	v_add_u32_e32 v148, 0xe00, v152
	v_ashrrev_i32_e32 v149, 31, v148
	v_lshl_add_u64 v[150:151], s[98:99], 0, v[148:149]
	v_lshl_add_u64 v[150:151], v[150:151], 1, s[0:1]
	global_load_ushort v119, v[150:151], off
	v_add_u32_e32 v152, 0, v24
	v_ashrrev_i32_e32 v153, 31, v152
	v_lshl_add_u64 v[150:151], s[100:101], 0, v[152:153]
	v_lshl_add_u64 v[148:149], v[150:151], 1, s[0:1]
	global_load_ushort v120, v[148:149], off
	v_add_u32_e32 v152, 0, v24
	v_add_u32_e32 v150, 0x200, v152
	v_ashrrev_i32_e32 v151, 31, v150
	v_lshl_add_u64 v[148:149], s[98:99], 0, v[150:151]
	v_lshl_add_u64 v[148:149], v[148:149], 1, s[0:1]
	global_load_ushort v121, v[148:149], off
	v_add_u32_e32 v152, 0, v24
	v_add_u32_e32 v148, 0xe00, v152
	v_ashrrev_i32_e32 v149, 31, v148
	v_lshl_add_u64 v[150:151], s[100:101], 0, v[148:149]
	v_lshl_add_u64 v[150:151], v[150:151], 1, s[0:1]
	global_load_ushort v122, v[150:151], off
	v_add_u32_e32 v154, 0, v24
	v_add_u32_e32 v152, 0x200, v154
	v_ashrrev_i32_e32 v153, 31, v152
	v_lshlrev_b64 v[148:149], 1, v[152:153]
	v_lshl_add_u64 v[150:151], s[30:31], 0, v[148:149]
	global_load_ushort v123, v[150:151], off
	v_add_u32_e32 v154, 0, v24
	v_add_u32_e32 v152, 0x200, v154
	v_ashrrev_i32_e32 v153, 31, v152
	v_lshl_add_u64 v[150:151], s[100:101], 0, v[152:153]
	v_lshl_add_u64 v[148:149], v[150:151], 1, s[0:1]
	global_load_ushort v124, v[148:149], off
	v_add_u32_e32 v152, 0, v24
	v_add_u32_e32 v150, 0x400, v152
	v_ashrrev_i32_e32 v151, 31, v150
	v_lshl_add_u64 v[148:149], s[98:99], 0, v[150:151]
	v_lshl_add_u64 v[148:149], v[148:149], 1, s[0:1]
	global_load_ushort v125, v[148:149], off
	v_add_u32_e32 v152, 0, v24
	v_add_u32_e32 v150, 0x200, v152
	v_ashrrev_i32_e32 v151, 31, v150
	v_lshlrev_b64 v[148:149], 1, v[150:151]
	v_lshl_add_u64 v[148:149], s[86:87], 0, v[148:149]
	global_load_ushort v126, v[148:149], off
	v_add_u32_e32 v154, 0, v24
	v_add_u32_e32 v152, 0x400, v154
	v_ashrrev_i32_e32 v153, 31, v152
	v_lshlrev_b64 v[148:149], 1, v[152:153]
	v_lshl_add_u64 v[150:151], s[30:31], 0, v[148:149]
	global_load_ushort v127, v[150:151], off
	v_add_u32_e32 v152, 0, v24
	v_add_u32_e32 v150, 0x400, v152
	v_ashrrev_i32_e32 v151, 31, v150
	v_lshlrev_b64 v[148:149], 1, v[150:151]
	v_lshl_add_u64 v[148:149], s[86:87], 0, v[148:149]
	global_load_ushort v128, v[148:149], off
	v_add_u32_e32 v154, 0, v24
	v_add_u32_e32 v152, 0x400, v154
	v_ashrrev_i32_e32 v153, 31, v152
	v_lshl_add_u64 v[150:151], s[100:101], 0, v[152:153]
	v_lshl_add_u64 v[148:149], v[150:151], 1, s[0:1]
	global_load_ushort v129, v[148:149], off
	v_add_u32_e32 v152, 0, v24
	v_add_u32_e32 v150, 0x600, v152
	v_ashrrev_i32_e32 v151, 31, v150
	v_lshl_add_u64 v[148:149], s[98:99], 0, v[150:151]
	v_lshl_add_u64 v[148:149], v[148:149], 1, s[0:1]
	global_load_ushort v130, v[148:149], off
	v_add_u32_e32 v154, 0, v24
	v_add_u32_e32 v152, 0x600, v154
	v_ashrrev_i32_e32 v153, 31, v152
	v_lshlrev_b64 v[148:149], 1, v[152:153]
	v_lshl_add_u64 v[150:151], s[30:31], 0, v[148:149]
	global_load_ushort v131, v[150:151], off
	v_add_u32_e32 v154, 0, v24
	v_add_u32_e32 v152, 0x600, v154
	v_ashrrev_i32_e32 v153, 31, v152
	v_lshl_add_u64 v[150:151], s[100:101], 0, v[152:153]
	v_lshl_add_u64 v[148:149], v[150:151], 1, s[0:1]
	global_load_ushort v132, v[148:149], off
	v_add_u32_e32 v152, 0, v24
	v_add_u32_e32 v150, 0x600, v152
	v_ashrrev_i32_e32 v151, 31, v150
	v_lshlrev_b64 v[148:149], 1, v[150:151]
	v_lshl_add_u64 v[148:149], s[86:87], 0, v[148:149]
	global_load_ushort v133, v[148:149], off
	v_add_u32_e32 v152, 0, v24
	v_add_u32_e32 v150, 0x800, v152
	v_ashrrev_i32_e32 v151, 31, v150
	v_lshl_add_u64 v[148:149], s[98:99], 0, v[150:151]
	v_lshl_add_u64 v[148:149], v[148:149], 1, s[0:1]
	global_load_ushort v134, v[148:149], off
	v_add_u32_e32 v154, 0, v24
	v_add_u32_e32 v152, 0x800, v154
	v_ashrrev_i32_e32 v153, 31, v152
	v_lshlrev_b64 v[148:149], 1, v[152:153]
	v_lshl_add_u64 v[150:151], s[30:31], 0, v[148:149]
	global_load_ushort v135, v[150:151], off
	v_add_u32_e32 v154, 0, v24
	v_add_u32_e32 v152, 0x800, v154
	v_ashrrev_i32_e32 v153, 31, v152
	v_lshl_add_u64 v[150:151], s[100:101], 0, v[152:153]
	v_lshl_add_u64 v[148:149], v[150:151], 1, s[0:1]
	global_load_ushort v136, v[148:149], off
	v_add_u32_e32 v152, 0, v24
	v_add_u32_e32 v150, 0x800, v152
	v_ashrrev_i32_e32 v151, 31, v150
	v_lshlrev_b64 v[148:149], 1, v[150:151]
	v_lshl_add_u64 v[148:149], s[86:87], 0, v[148:149]
	global_load_ushort v137, v[148:149], off
	v_add_u32_e32 v152, 0, v24
	v_add_u32_e32 v150, 0xa00, v152
	v_ashrrev_i32_e32 v151, 31, v150
	v_lshl_add_u64 v[148:149], s[98:99], 0, v[150:151]
	v_lshl_add_u64 v[148:149], v[148:149], 1, s[0:1]
	global_load_ushort v138, v[148:149], off
	v_add_u32_e32 v154, 0, v24
	v_add_u32_e32 v152, 0xa00, v154
	v_ashrrev_i32_e32 v153, 31, v152
	v_lshlrev_b64 v[148:149], 1, v[152:153]
	v_lshl_add_u64 v[150:151], s[30:31], 0, v[148:149]
	global_load_ushort v139, v[150:151], off
	v_add_u32_e32 v154, 0, v24
	v_add_u32_e32 v152, 0xa00, v154
	v_ashrrev_i32_e32 v153, 31, v152
	v_lshl_add_u64 v[150:151], s[100:101], 0, v[152:153]
	v_lshl_add_u64 v[148:149], v[150:151], 1, s[0:1]
	global_load_ushort v140, v[148:149], off
	v_add_u32_e32 v152, 0, v24
	v_add_u32_e32 v150, 0xa00, v152
	v_ashrrev_i32_e32 v151, 31, v150
	v_lshlrev_b64 v[148:149], 1, v[150:151]
	v_lshl_add_u64 v[148:149], s[86:87], 0, v[148:149]
	global_load_ushort v141, v[148:149], off
	v_add_u32_e32 v152, 0, v24
	v_add_u32_e32 v150, 0xc00, v152
	v_ashrrev_i32_e32 v151, 31, v150
	v_lshl_add_u64 v[148:149], s[98:99], 0, v[150:151]
	v_lshl_add_u64 v[148:149], v[148:149], 1, s[0:1]
	global_load_ushort v142, v[148:149], off
	v_add_u32_e32 v154, 0, v24
	v_add_u32_e32 v152, 0xc00, v154
	v_ashrrev_i32_e32 v153, 31, v152
	v_lshlrev_b64 v[148:149], 1, v[152:153]
	v_lshl_add_u64 v[150:151], s[30:31], 0, v[148:149]
	global_load_ushort v143, v[150:151], off
	v_add_u32_e32 v152, 0, v24
	v_add_u32_e32 v150, 0xc00, v152
	v_ashrrev_i32_e32 v151, 31, v150
	v_lshlrev_b64 v[148:149], 1, v[150:151]
	v_lshl_add_u64 v[148:149], s[86:87], 0, v[148:149]
	global_load_ushort v144, v[148:149], off
	v_add_u32_e32 v154, 0, v24
	v_add_u32_e32 v152, 0xc00, v154
	v_ashrrev_i32_e32 v153, 31, v152
	v_lshl_add_u64 v[150:151], s[100:101], 0, v[152:153]
	v_lshl_add_u64 v[148:149], v[150:151], 1, s[0:1]
	global_load_ushort v145, v[148:149], off
	v_add_u32_e32 v154, 0, v24
	v_add_u32_e32 v152, 0xe00, v154
	v_ashrrev_i32_e32 v153, 31, v152
	v_lshlrev_b64 v[148:149], 1, v[152:153]
	v_lshl_add_u64 v[150:151], s[30:31], 0, v[148:149]
	global_load_ushort v146, v[150:151], off
	v_add_u32_e32 v152, 0, v24
	v_add_u32_e32 v150, 0xe00, v152
	v_ashrrev_i32_e32 v151, 31, v150
	v_lshlrev_b64 v[148:149], 1, v[150:151]
	v_lshl_add_u64 v[148:149], s[86:87], 0, v[148:149]
	global_load_ushort v147, v[148:149], off
	v_readlane_b32 vcc_lo, v253, 29
	v_readlane_b32 vcc_hi, v253, 30
	s_lshl_b64 s[98:99], s[28:29], 2
	s_add_u32 s98, vcc_lo, s98
	s_addc_u32 s99, vcc_hi, s99
	global_load_dwordx2 v[156:157], v1, s[98:99]
	v_lshlrev_b32_e32 v220, 16, v168
	v_and_b32_e32 v221, 0xffff0000, v168
	v_bfe_u32 v222, v218, 16, 1
	v_bfe_u32 v223, v219, 16, 1
	v_add3_u32 v222, v218, v222, v234
	v_add3_u32 v223, v219, v223, v234
	v_lshrrev_b32_e32 v222, 16, v222
	v_and_or_b32 v222, v223, v235, v222
	global_store_dword v[226:227], v222, off
	v_pk_fma_f32 v[218:219], v[186:187], v[218:219], v[220:221]
	v_lshl_add_u64 v[226:227], v[226:227], 0, v[230:231]
	v_lshlrev_b32_e32 v220, 16, v169
	v_and_b32_e32 v221, 0xffff0000, v169
	v_bfe_u32 v222, v218, 16, 1
	v_bfe_u32 v223, v219, 16, 1
	v_add3_u32 v222, v218, v222, v234
	v_add3_u32 v223, v219, v223, v234
	v_lshrrev_b32_e32 v222, 16, v222
	v_and_or_b32 v222, v223, v235, v222
	global_store_dword v[226:227], v222, off
	v_pk_fma_f32 v[218:219], v[188:189], v[218:219], v[220:221]
	v_lshl_add_u64 v[226:227], v[226:227], 0, v[230:231]
	v_lshlrev_b32_e32 v220, 16, v170
	v_and_b32_e32 v221, 0xffff0000, v170
	v_bfe_u32 v222, v218, 16, 1
	v_bfe_u32 v223, v219, 16, 1
	v_add3_u32 v222, v218, v222, v234
	v_add3_u32 v223, v219, v223, v234
	v_lshrrev_b32_e32 v222, 16, v222
	v_and_or_b32 v222, v223, v235, v222
	global_store_dword v[226:227], v222, off
	v_pk_fma_f32 v[218:219], v[190:191], v[218:219], v[220:221]
	v_lshl_add_u64 v[226:227], v[226:227], 0, v[230:231]
	v_lshlrev_b32_e32 v220, 16, v171
	v_and_b32_e32 v221, 0xffff0000, v171
	v_bfe_u32 v222, v218, 16, 1
	v_bfe_u32 v223, v219, 16, 1
	v_add3_u32 v222, v218, v222, v234
	v_add3_u32 v223, v219, v223, v234
	v_lshrrev_b32_e32 v222, 16, v222
	v_and_or_b32 v222, v223, v235, v222
	global_store_dword v[226:227], v222, off
	v_pk_fma_f32 v[218:219], v[192:193], v[218:219], v[220:221]
	v_lshl_add_u64 v[226:227], v[226:227], 0, v[230:231]
	v_lshlrev_b32_e32 v220, 16, v172
	v_and_b32_e32 v221, 0xffff0000, v172
	v_bfe_u32 v222, v218, 16, 1
	v_bfe_u32 v223, v219, 16, 1
	v_add3_u32 v222, v218, v222, v234
	v_add3_u32 v223, v219, v223, v234
	v_lshrrev_b32_e32 v222, 16, v222
	v_and_or_b32 v222, v223, v235, v222
	global_store_dword v[226:227], v222, off
	v_pk_fma_f32 v[218:219], v[194:195], v[218:219], v[220:221]
	v_lshl_add_u64 v[226:227], v[226:227], 0, v[230:231]
	v_lshlrev_b32_e32 v220, 16, v173
	v_and_b32_e32 v221, 0xffff0000, v173
	v_bfe_u32 v222, v218, 16, 1
	v_bfe_u32 v223, v219, 16, 1
	v_add3_u32 v222, v218, v222, v234
	v_add3_u32 v223, v219, v223, v234
	v_lshrrev_b32_e32 v222, 16, v222
	v_and_or_b32 v222, v223, v235, v222
	global_store_dword v[226:227], v222, off
	v_pk_fma_f32 v[218:219], v[196:197], v[218:219], v[220:221]
	v_lshl_add_u64 v[226:227], v[226:227], 0, v[230:231]
	v_lshlrev_b32_e32 v220, 16, v174
	v_and_b32_e32 v221, 0xffff0000, v174
	v_bfe_u32 v222, v218, 16, 1
	v_bfe_u32 v223, v219, 16, 1
	v_add3_u32 v222, v218, v222, v234
	v_add3_u32 v223, v219, v223, v234
	v_lshrrev_b32_e32 v222, 16, v222
	v_and_or_b32 v222, v223, v235, v222
	global_store_dword v[226:227], v222, off
	v_pk_fma_f32 v[218:219], v[198:199], v[218:219], v[220:221]
	v_lshl_add_u64 v[226:227], v[226:227], 0, v[230:231]
	v_lshlrev_b32_e32 v220, 16, v175
	v_and_b32_e32 v221, 0xffff0000, v175
	v_bfe_u32 v222, v218, 16, 1
	v_bfe_u32 v223, v219, 16, 1
	v_add3_u32 v222, v218, v222, v234
	v_add3_u32 v223, v219, v223, v234
	v_lshrrev_b32_e32 v222, 16, v222
	v_and_or_b32 v222, v223, v235, v222
	global_store_dword v[226:227], v222, off
	v_pk_fma_f32 v[218:219], v[200:201], v[218:219], v[220:221]
	v_lshl_add_u64 v[226:227], v[226:227], 0, v[230:231]
	v_lshlrev_b32_e32 v220, 16, v176
	v_and_b32_e32 v221, 0xffff0000, v176
	v_bfe_u32 v222, v218, 16, 1
	v_bfe_u32 v223, v219, 16, 1
	v_add3_u32 v222, v218, v222, v234
	v_add3_u32 v223, v219, v223, v234
	v_lshrrev_b32_e32 v222, 16, v222
	v_and_or_b32 v222, v223, v235, v222
	global_store_dword v[226:227], v222, off
	v_pk_fma_f32 v[218:219], v[202:203], v[218:219], v[220:221]
	v_lshl_add_u64 v[226:227], v[226:227], 0, v[230:231]
	v_lshlrev_b32_e32 v220, 16, v177
	v_and_b32_e32 v221, 0xffff0000, v177
	v_bfe_u32 v222, v218, 16, 1
	v_bfe_u32 v223, v219, 16, 1
	v_add3_u32 v222, v218, v222, v234
	v_add3_u32 v223, v219, v223, v234
	v_lshrrev_b32_e32 v222, 16, v222
	v_and_or_b32 v222, v223, v235, v222
	global_store_dword v[226:227], v222, off
	v_pk_fma_f32 v[218:219], v[204:205], v[218:219], v[220:221]
	v_lshl_add_u64 v[226:227], v[226:227], 0, v[230:231]
	v_lshlrev_b32_e32 v220, 16, v180
	v_and_b32_e32 v221, 0xffff0000, v180
	v_bfe_u32 v222, v218, 16, 1
	v_bfe_u32 v223, v219, 16, 1
	v_add3_u32 v222, v218, v222, v234
	v_add3_u32 v223, v219, v223, v234
	v_lshrrev_b32_e32 v222, 16, v222
	v_and_or_b32 v222, v223, v235, v222
	global_store_dword v[226:227], v222, off
	v_pk_fma_f32 v[218:219], v[206:207], v[218:219], v[220:221]
	v_lshl_add_u64 v[226:227], v[226:227], 0, v[230:231]
	v_lshlrev_b32_e32 v220, 16, v181
	v_and_b32_e32 v221, 0xffff0000, v181
	v_bfe_u32 v222, v218, 16, 1
	v_bfe_u32 v223, v219, 16, 1
	v_add3_u32 v222, v218, v222, v234
	v_add3_u32 v223, v219, v223, v234
	v_lshrrev_b32_e32 v222, 16, v222
	v_and_or_b32 v222, v223, v235, v222
	global_store_dword v[226:227], v222, off
	v_pk_fma_f32 v[218:219], v[208:209], v[218:219], v[220:221]
	v_lshl_add_u64 v[226:227], v[226:227], 0, v[230:231]
	v_lshlrev_b32_e32 v220, 16, v182
	v_and_b32_e32 v221, 0xffff0000, v182
	v_bfe_u32 v222, v218, 16, 1
	v_bfe_u32 v223, v219, 16, 1
	v_add3_u32 v222, v218, v222, v234
	v_add3_u32 v223, v219, v223, v234
	v_lshrrev_b32_e32 v222, 16, v222
	v_and_or_b32 v222, v223, v235, v222
	global_store_dword v[226:227], v222, off
	v_pk_fma_f32 v[218:219], v[210:211], v[218:219], v[220:221]
	v_lshl_add_u64 v[226:227], v[226:227], 0, v[230:231]
	v_lshlrev_b32_e32 v220, 16, v183
	v_and_b32_e32 v221, 0xffff0000, v183
	v_bfe_u32 v222, v218, 16, 1
	v_bfe_u32 v223, v219, 16, 1
	v_add3_u32 v222, v218, v222, v234
	v_add3_u32 v223, v219, v223, v234
	v_lshrrev_b32_e32 v222, 16, v222
	v_and_or_b32 v222, v223, v235, v222
	global_store_dword v[226:227], v222, off
	v_pk_fma_f32 v[218:219], v[212:213], v[218:219], v[220:221]
	v_lshl_add_u64 v[226:227], v[226:227], 0, v[230:231]
	v_lshlrev_b32_e32 v220, 16, v184
	v_and_b32_e32 v221, 0xffff0000, v184
	v_bfe_u32 v222, v218, 16, 1
	v_bfe_u32 v223, v219, 16, 1
	v_add3_u32 v222, v218, v222, v234
	v_add3_u32 v223, v219, v223, v234
	v_lshrrev_b32_e32 v222, 16, v222
	v_and_or_b32 v222, v223, v235, v222
	global_store_dword v[226:227], v222, off
	v_pk_fma_f32 v[218:219], v[214:215], v[218:219], v[220:221]
	v_lshl_add_u64 v[226:227], v[226:227], 0, v[230:231]
	v_lshlrev_b32_e32 v220, 16, v185
	v_and_b32_e32 v221, 0xffff0000, v185
	v_bfe_u32 v222, v218, 16, 1
	v_bfe_u32 v223, v219, 16, 1
	v_add3_u32 v222, v218, v222, v234
	v_add3_u32 v223, v219, v223, v234
	v_lshrrev_b32_e32 v222, 16, v222
	v_and_or_b32 v222, v223, v235, v222
	global_store_dword v[226:227], v222, off
	v_pk_fma_f32 v[218:219], v[216:217], v[218:219], v[220:221]
	v_lshl_add_u64 v[226:227], v[226:227], 0, v[230:231]
	s_nop 0
	v_add_f32_e32 v0, 0, v8
	v_add_f32_e32 v0, v0, v9
	v_add_f32_e32 v0, v0, v10
	v_add_f32_e32 v0, v0, v11
	v_add_f32_e32 v0, v0, v4
	v_add_f32_e32 v0, v0, v5
	v_add_f32_e32 v0, v0, v6
	v_add_f32_e32 v0, v0, v7
	v_div_scale_f32 v3, s[2:3], v0, v0, 1.0
	v_rcp_f32_e32 v4, v3
	v_add_f32_e32 v2, 0, v16
	v_add_f32_e32 v2, v2, v17
	v_add_f32_e32 v2, v2, v18
	v_fma_f32 v5, -v3, v4, 1.0
	v_fmac_f32_e32 v4, v5, v4
	v_div_scale_f32 v5, vcc, 1.0, v0, 1.0
	v_add_f32_e32 v2, v2, v19
	v_mul_f32_e32 v6, v5, v4
	v_add_f32_e32 v2, v2, v12
	v_fma_f32 v7, -v3, v6, v5
	v_add_f32_e32 v2, v2, v13
	v_fmac_f32_e32 v6, v7, v4
	v_add_f32_e32 v2, v2, v14
	v_fma_f32 v3, -v3, v6, v5
	v_add_f32_e32 v2, v2, v15
	v_div_fmas_f32 v3, v3, v4, v6
	v_div_fixup_f32 v0, v3, v0, 1.0
	v_div_scale_f32 v3, s[2:3], v2, v2, 1.0
	v_rcp_f32_e32 v4, v3
	v_readlane_b32 s52, v253, 23
	s_lshl_b64 s[2:3], s[28:29], 2
	v_readlane_b32 s58, v253, 29
	v_fma_f32 v5, -v3, v4, 1.0
	v_fmac_f32_e32 v4, v5, v4
	v_div_scale_f32 v5, vcc, 1.0, v2, 1.0
	v_mul_f32_e32 v6, v5, v4
	v_fma_f32 v7, -v3, v6, v5
	v_fmac_f32_e32 v6, v7, v4
	v_fma_f32 v3, -v3, v6, v5
	v_readlane_b32 s59, v253, 30
	s_add_u32 s2, s58, s2
	v_div_fmas_f32 v3, v3, v4, v6
	s_addc_u32 s3, s59, s3
	v_div_fixup_f32 v25, v3, v2, 1.0
	s_waitcnt lgkmcnt(0)
	s_barrier
	s_nop 0
	s_lshl_b64 s[2:3], s[28:29], 13
	s_lshl_b64 s[10:11], s[10:11], 13
	s_mov_b32 s20, 0
	s_mov_b64 s[12:13], -1
	v_readlane_b32 s53, v253, 24
	v_readlane_b32 s54, v253, 25
	v_readlane_b32 s55, v253, 26
	v_readlane_b32 s56, v253, 27
	v_readlane_b32 s57, v253, 28
	v_readlane_b32 s60, v253, 31
	v_readlane_b32 s61, v253, 32
	v_readlane_b32 s62, v253, 33
	v_readlane_b32 s63, v253, 34
	v_readlane_b32 s64, v253, 35
	v_readlane_b32 s65, v253, 36
	v_readlane_b32 s66, v253, 37
	v_readlane_b32 s67, v253, 38

.Lmy_ff_skip:
	s_waitcnt vmcnt(0)
	v_mov_b32_e32 v2, v156
	v_mov_b32_e32 v3, v157
	v_add_u32_e32 v82, s20, v24
	v_ashrrev_i32_e32 v83, 31, v82
	v_lshlrev_b64 v[4:5], 1, v[82:83]
	v_lshl_add_u64 v[20:21], s[30:31], 0, v[4:5]
	v_lshl_add_u64 v[6:7], s[2:3], 0, v[82:83]
	v_lshl_add_u64 v[4:5], s[86:87], 0, v[4:5]
	v_lshl_add_u64 v[6:7], v[6:7], 1, s[0:1]
	v_add_u32_e32 v54, 0xe00, v82
	v_ashrrev_i32_e32 v55, 31, v54
	v_lshl_add_u64 v[80:81], s[2:3], 0, v[54:55]
	v_lshl_add_u64 v[8:9], s[10:11], 0, v[82:83]
	v_lshl_add_u64 v[80:81], v[80:81], 1, s[0:1]
	v_add_u32_e32 v42, 0x200, v82
	v_ashrrev_i32_e32 v43, 31, v42
	v_lshl_add_u64 v[114:115], s[10:11], 0, v[54:55]
	v_lshl_add_u64 v[114:115], v[114:115], 1, s[0:1]
	v_add_u32_e32 v44, 0x400, v82
	v_ashrrev_i32_e32 v45, 31, v44
	v_add_u32_e32 v46, 0x600, v82
	v_ashrrev_i32_e32 v47, 31, v46
	v_add_u32_e32 v48, 0x800, v82
	v_ashrrev_i32_e32 v49, 31, v48
	v_add_u32_e32 v50, 0xa00, v82
	v_ashrrev_i32_e32 v51, 31, v50
	v_add_u32_e32 v52, 0xc00, v82
	v_ashrrev_i32_e32 v53, 31, v52
	v_lshl_add_u64 v[40:41], s[10:11], 0, v[52:53]
	v_lshl_add_u32 v111, s20, 3, v90
	s_movk_i32 s20, 0x1000
	s_and_b64 vcc, exec, s[12:13]
	s_mov_b64 s[12:13], 0
	v_lshlrev_b32_e32 v57, 16, v116
	v_ashrrev_i32_e32 v81, 5, v82
	v_lshl_add_u32 v81, v81, 3, v111
	ds_read_b64 v[82:83], v81
	s_waitcnt lgkmcnt(0)
	v_mul_f32_e32 v81, 0x38800000, v82
	v_mul_f32_e32 v81, v0, v81
	v_fmac_f32_e32 v81, v2, v57
	v_lshlrev_b32_e32 v73, 16, v117
	v_lshl_add_u64 v[6:7], v[8:9], 1, s[0:1]
	v_lshl_add_u64 v[8:9], s[2:3], 0, v[42:43]
	v_lshl_add_u64 v[8:9], v[8:9], 1, s[0:1]
	v_mul_f32_e32 v57, v81, v73
	v_bfe_u32 v73, v57, 16, 1
	v_add3_u32 v57, v57, v73, s45
	v_lshlrev_b32_e32 v56, 16, v118
	v_lshlrev_b32_e32 v80, 16, v119
	v_lshl_add_u64 v[10:11], s[10:11], 0, v[42:43]
	v_lshlrev_b32_e32 v65, 16, v120
	v_lshlrev_b64 v[6:7], 1, v[42:43]
	v_lshl_add_u64 v[22:23], s[30:31], 0, v[6:7]
	v_lshl_add_u64 v[6:7], s[86:87], 0, v[6:7]
	v_lshlrev_b32_e32 v74, 16, v121
	v_lshl_add_u64 v[8:9], v[10:11], 1, s[0:1]
	v_lshl_add_u64 v[10:11], s[2:3], 0, v[44:45]
	v_lshl_add_u64 v[10:11], v[10:11], 1, s[0:1]
	v_lshlrev_b32_e32 v72, 16, v122
	v_lshlrev_b32_e32 v58, 16, v123
	v_lshlrev_b32_e32 v66, 16, v124
	v_lshlrev_b64 v[8:9], 1, v[44:45]
	v_lshl_add_u64 v[30:31], s[30:31], 0, v[8:9]
	v_lshl_add_u64 v[8:9], s[86:87], 0, v[8:9]
	v_lshlrev_b32_e32 v75, 16, v125
	v_lshlrev_b32_e32 v43, 16, v126
	v_lshl_add_u64 v[12:13], s[10:11], 0, v[44:45]
	v_lshl_add_u64 v[10:11], v[12:13], 1, s[0:1]
	v_lshl_add_u64 v[12:13], s[2:3], 0, v[46:47]
	v_lshl_add_u64 v[12:13], v[12:13], 1, s[0:1]
	v_lshlrev_b32_e32 v59, 16, v127
	s_nop 0
	s_nop 0
	v_lshlrev_b32_e32 v45, 16, v128
	v_lshl_add_u64 v[14:15], s[10:11], 0, v[46:47]
	v_lshlrev_b32_e32 v67, 16, v129
	v_lshlrev_b64 v[10:11], 1, v[46:47]
	v_lshlrev_b32_e32 v76, 16, v130
	v_lshl_add_u64 v[32:33], s[30:31], 0, v[10:11]
	v_lshl_add_u64 v[10:11], s[86:87], 0, v[10:11]
	v_lshl_add_u64 v[12:13], v[14:15], 1, s[0:1]
	v_lshl_add_u64 v[14:15], s[2:3], 0, v[48:49]
	v_lshl_add_u64 v[14:15], v[14:15], 1, s[0:1]
	v_lshlrev_b32_e32 v60, 16, v131
	s_nop 0
	v_lshlrev_b32_e32 v68, 16, v132
	v_lshlrev_b64 v[12:13], 1, v[48:49]
	v_lshl_add_u64 v[34:35], s[30:31], 0, v[12:13]
	v_lshl_add_u64 v[12:13], s[86:87], 0, v[12:13]
	v_lshlrev_b32_e32 v47, 16, v133
	v_lshl_add_u64 v[16:17], s[10:11], 0, v[48:49]
	v_lshlrev_b32_e32 v77, 16, v134
	v_lshl_add_u64 v[14:15], v[16:17], 1, s[0:1]
	v_lshl_add_u64 v[16:17], s[2:3], 0, v[50:51]
	v_lshl_add_u64 v[16:17], v[16:17], 1, s[0:1]
	v_lshlrev_b32_e32 v61, 16, v135
	s_nop 0
	v_lshlrev_b32_e32 v69, 16, v136
	v_lshlrev_b64 v[14:15], 1, v[50:51]
	v_lshlrev_b32_e32 v49, 16, v137
	v_lshl_add_u64 v[18:19], s[10:11], 0, v[50:51]
	v_lshlrev_b32_e32 v78, 16, v138
	v_lshl_add_u64 v[36:37], s[30:31], 0, v[14:15]
	v_lshl_add_u64 v[14:15], s[86:87], 0, v[14:15]
	v_lshl_add_u64 v[16:17], v[18:19], 1, s[0:1]
	v_lshl_add_u64 v[18:19], s[2:3], 0, v[52:53]
	v_lshl_add_u64 v[18:19], v[18:19], 1, s[0:1]
	v_lshlrev_b32_e32 v62, 16, v139
	s_nop 0
	v_lshlrev_b32_e32 v70, 16, v140
	v_lshlrev_b64 v[16:17], 1, v[52:53]
	v_lshlrev_b32_e32 v51, 16, v141
	v_lshl_add_u64 v[38:39], s[30:31], 0, v[16:17]
	v_lshl_add_u64 v[16:17], s[86:87], 0, v[16:17]
	v_lshlrev_b32_e32 v79, 16, v142
	v_lshl_add_u64 v[18:19], v[40:41], 1, s[0:1]
	v_lshlrev_b32_e32 v63, 16, v143
	s_nop 0
	v_lshlrev_b32_e32 v53, 16, v144
	v_lshlrev_b32_e32 v71, 16, v145
	v_lshlrev_b64 v[18:19], 1, v[54:55]
	v_lshl_add_u64 v[40:41], s[30:31], 0, v[18:19]
	v_lshl_add_u64 v[18:19], s[86:87], 0, v[18:19]
	v_lshlrev_b32_e32 v64, 16, v146
	v_lshlrev_b32_e32 v55, 16, v147
	global_store_short_d16_hi v[20:21], v57, off
	v_mul_f32_e32 v20, 0x38800000, v83
	v_mul_f32_e32 v20, v25, v20
	v_fmac_f32_e32 v20, v3, v56
	v_mul_f32_e32 v20, v20, v65
	v_bfe_u32 v21, v20, 16, 1
	v_add3_u32 v20, v20, v21, s45
	global_store_short_d16_hi v[4:5], v20, off
	v_ashrrev_i32_e32 v4, 5, v42
	v_lshl_add_u32 v4, v4, 3, v111
	ds_read_b64 v[4:5], v4 offset:4096
	s_waitcnt lgkmcnt(0)
	v_mul_f32_e32 v4, 0x38800000, v4
	v_mul_f32_e32 v4, v0, v4
	v_fmac_f32_e32 v4, v2, v58
	v_mul_f32_e32 v4, v4, v74
	v_bfe_u32 v20, v4, 16, 1
	v_add3_u32 v4, v4, v20, s45
	global_store_short_d16_hi v[22:23], v4, off
	v_mul_f32_e32 v4, 0x38800000, v5
	v_mul_f32_e32 v4, v25, v4
	v_fmac_f32_e32 v4, v3, v43
	v_mul_f32_e32 v4, v4, v66
	v_bfe_u32 v5, v4, 16, 1
	v_add3_u32 v4, v4, v5, s45
	global_store_short_d16_hi v[6:7], v4, off
	v_ashrrev_i32_e32 v4, 5, v44
	v_lshl_add_u32 v4, v4, 3, v111
	ds_read_b64 v[4:5], v4 offset:8192
	s_waitcnt lgkmcnt(0)
	v_mul_f32_e32 v4, 0x38800000, v4
	v_mul_f32_e32 v4, v0, v4
	v_fmac_f32_e32 v4, v2, v59
	v_mul_f32_e32 v4, v4, v75
	v_bfe_u32 v6, v4, 16, 1
	v_add3_u32 v4, v4, v6, s45
	global_store_short_d16_hi v[30:31], v4, off
	v_mul_f32_e32 v4, 0x38800000, v5
	v_mul_f32_e32 v4, v25, v4
	v_fmac_f32_e32 v4, v3, v45
	v_mul_f32_e32 v4, v4, v67
	v_bfe_u32 v5, v4, 16, 1
	v_add3_u32 v4, v4, v5, s45
	global_store_short_d16_hi v[8:9], v4, off
	v_ashrrev_i32_e32 v4, 5, v46
	v_lshl_add_u32 v4, v4, 3, v111
	ds_read_b64 v[4:5], v4 offset:12288
	s_waitcnt lgkmcnt(0)
	v_mul_f32_e32 v4, 0x38800000, v4
	v_mul_f32_e32 v4, v0, v4
	v_fmac_f32_e32 v4, v2, v60
	v_mul_f32_e32 v4, v4, v76
	v_bfe_u32 v6, v4, 16, 1
	v_add3_u32 v4, v4, v6, s45
	global_store_short_d16_hi v[32:33], v4, off
	v_mul_f32_e32 v4, 0x38800000, v5
	v_mul_f32_e32 v4, v25, v4
	v_fmac_f32_e32 v4, v3, v47
	v_mul_f32_e32 v4, v4, v68
	v_bfe_u32 v5, v4, 16, 1
	v_add3_u32 v4, v4, v5, s45
	global_store_short_d16_hi v[10:11], v4, off
	v_ashrrev_i32_e32 v4, 5, v48
	v_lshl_add_u32 v4, v4, 3, v111
	ds_read_b64 v[4:5], v4 offset:16384
	s_waitcnt lgkmcnt(0)
	v_mul_f32_e32 v4, 0x38800000, v4
	v_mul_f32_e32 v4, v0, v4
	v_fmac_f32_e32 v4, v2, v61
	v_mul_f32_e32 v4, v4, v77
	v_bfe_u32 v6, v4, 16, 1
	v_add3_u32 v4, v4, v6, s45
	global_store_short_d16_hi v[34:35], v4, off
	v_mul_f32_e32 v4, 0x38800000, v5
	v_mul_f32_e32 v4, v25, v4
	v_fmac_f32_e32 v4, v3, v49
	v_mul_f32_e32 v4, v4, v69
	v_bfe_u32 v5, v4, 16, 1
	v_add3_u32 v4, v4, v5, s45
	global_store_short_d16_hi v[12:13], v4, off
	v_ashrrev_i32_e32 v4, 5, v50
	v_lshl_add_u32 v4, v4, 3, v111
	ds_read_b64 v[4:5], v4 offset:20480
	s_waitcnt lgkmcnt(0)
	v_mul_f32_e32 v4, 0x38800000, v4
	v_mul_f32_e32 v4, v0, v4
	v_fmac_f32_e32 v4, v2, v62
	v_mul_f32_e32 v4, v4, v78
	v_bfe_u32 v6, v4, 16, 1
	v_add3_u32 v4, v4, v6, s45
	global_store_short_d16_hi v[36:37], v4, off
	v_mul_f32_e32 v4, 0x38800000, v5
	v_mul_f32_e32 v4, v25, v4
	v_fmac_f32_e32 v4, v3, v51
	v_mul_f32_e32 v4, v4, v70
	v_bfe_u32 v5, v4, 16, 1
	v_add3_u32 v4, v4, v5, s45
	global_store_short_d16_hi v[14:15], v4, off
	v_ashrrev_i32_e32 v4, 5, v52
	v_lshl_add_u32 v4, v4, 3, v111
	ds_read_b64 v[4:5], v4 offset:24576
	s_waitcnt lgkmcnt(0)
	v_mul_f32_e32 v4, 0x38800000, v4
	v_mul_f32_e32 v4, v0, v4
	v_fmac_f32_e32 v4, v2, v63
	v_mul_f32_e32 v4, v4, v79
	v_bfe_u32 v6, v4, 16, 1
	v_add3_u32 v4, v4, v6, s45
	global_store_short_d16_hi v[38:39], v4, off
	v_mul_f32_e32 v4, 0x38800000, v5
	v_mul_f32_e32 v4, v25, v4
	v_fmac_f32_e32 v4, v3, v53
	v_mul_f32_e32 v4, v4, v71
	v_bfe_u32 v5, v4, 16, 1
	v_add3_u32 v4, v4, v5, s45
	global_store_short_d16_hi v[16:17], v4, off
	v_ashrrev_i32_e32 v4, 5, v54
	v_lshl_add_u32 v4, v4, 3, v111
	ds_read_b64 v[4:5], v4 offset:28672
	s_waitcnt lgkmcnt(0)
	v_mul_f32_e32 v4, 0x38800000, v4
	v_mul_f32_e32 v4, v0, v4
	v_fmac_f32_e32 v4, v2, v64
	v_mul_f32_e32 v4, v4, v80
	v_bfe_u32 v6, v4, 16, 1
	v_add3_u32 v4, v4, v6, s45
	global_store_short_d16_hi v[40:41], v4, off
	v_mul_f32_e32 v4, 0x38800000, v5
	v_mul_f32_e32 v4, v25, v4
	v_fmac_f32_e32 v4, v3, v55
	v_mul_f32_e32 v4, v4, v72
	v_bfe_u32 v5, v4, 16, 1
	v_add3_u32 v4, v4, v5, s45
	global_store_short_d16_hi v[18:19], v4, off
	s_cbranch_vccnz .LBB0_704
	v_readlane_b32 s2, v253, 3
	s_add_i32 s33, s33, s2
	s_cmpk_gt_i32 s33, 0x1ff
	s_barrier
	v_readlane_b32 s3, v253, 4
	s_cbranch_scc0 .LBB0_617
